# quarter-unit K loop with four half-stage slots per operand: LDS-DMA prefetch distance three K steps (was one), counted vmcnt(8); entry issues K steps 2-3, next unit's first two steps one iteration ear
# speedup vs baseline: 1.0022x; 1.0022x over previous
.Lq5_entry:
	v_mov_b32_e32 v4, 0
	v_mov_b32_e32 v5, 0
	v_mov_b32_e32 v6, 0
	v_mov_b32_e32 v7, 0
	v_mov_b32_e32 v8, 0
	v_mov_b32_e32 v9, 0
	v_mov_b32_e32 v10, 0
	v_mov_b32_e32 v11, 0
	v_mov_b32_e32 v12, 0
	v_mov_b32_e32 v13, 0
	v_mov_b32_e32 v14, 0
	v_mov_b32_e32 v15, 0
	v_mov_b32_e32 v16, 0
	v_mov_b32_e32 v17, 0
	v_mov_b32_e32 v18, 0
	v_mov_b32_e32 v19, 0
	v_mov_b32_e32 v20, 0
	v_mov_b32_e32 v21, 0
	v_mov_b32_e32 v22, 0
	v_mov_b32_e32 v23, 0
	v_mov_b32_e32 v24, 0
	v_mov_b32_e32 v25, 0
	v_mov_b32_e32 v26, 0
	v_mov_b32_e32 v27, 0
	v_mov_b32_e32 v28, 0
	v_mov_b32_e32 v29, 0
	v_mov_b32_e32 v30, 0
	v_mov_b32_e32 v31, 0
	v_mov_b32_e32 v32, 0
	v_mov_b32_e32 v33, 0
	v_mov_b32_e32 v34, 0
	v_mov_b32_e32 v35, 0
	v_mov_b32_e32 v36, 0
	v_mov_b32_e32 v37, 0
	v_mov_b32_e32 v38, 0
	v_mov_b32_e32 v39, 0
	v_mov_b32_e32 v40, 0
	v_mov_b32_e32 v41, 0
	v_mov_b32_e32 v42, 0
	v_mov_b32_e32 v43, 0
	v_mov_b32_e32 v44, 0
	v_mov_b32_e32 v45, 0
	v_mov_b32_e32 v46, 0
	v_mov_b32_e32 v47, 0
	v_mov_b32_e32 v48, 0
	v_mov_b32_e32 v49, 0
	v_mov_b32_e32 v50, 0
	v_mov_b32_e32 v51, 0
	v_cmp_ne_u32_e64 s[2:3], 1, v217
	s_andn2_b64 vcc, exec, s[26:27]
	s_add_u32 s56, s34, 0xfff80080
	s_addc_u32 s57, s35, -1
	s_cmp_eq_u32 s77, 12
	s_cselect_b32 s59, s39, s57
	s_cselect_b32 s58, s38, s56
	s_cselect_b32 s57, s47, s41
	s_cselect_b32 s56, s46, s18
	s_mov_b32 m0, s51
	v_lshl_add_u64 v[2:3], s[56:57], 0, v[198:199]
	s_add_u32 s78, s56, 0x80000
	global_load_lds_dwordx4 v[2:3], off
	v_lshl_add_u64 v[204:205], s[56:57], 0, v[196:197]
	s_mov_b32 m0, s60
	s_addc_u32 s79, s57, 0
	global_load_lds_dwordx4 v[204:205], off
	v_lshl_add_u64 v[206:207], s[78:79], 0, v[198:199]
	s_mov_b32 m0, s66
	v_lshl_add_u64 v[208:209], s[58:59], 0, v[196:197]
	v_lshl_add_u64 v[206:207], s[78:79], 0, v[196:197]
	s_mov_b32 m0, s67
	s_and_b64 vcc, exec, s[2:3]
	v_lshl_add_u64 v[206:207], s[58:59], 0, v[198:199]
	s_mov_b32 m0, s62
	s_nop 0
	global_load_lds_dwordx4 v[206:207], off
	s_mov_b32 m0, s63
	s_nop 0
	global_load_lds_dwordx4 v[208:209], off
	s_and_b64 vcc, exec, s[2:3]
	s_mov_b32 m0, s70
	v_lshl_add_u64 v[2:3], v[2:3], 0, s[16:17]
	s_add_u32 s56, s56, 0x80080
	global_load_lds_dwordx4 v[2:3], off
	v_lshl_add_u64 v[2:3], v[204:205], 0, s[16:17]
	s_mov_b32 m0, s71
	s_addc_u32 s57, s57, 0
	global_load_lds_dwordx4 v[2:3], off
	v_lshl_add_u64 v[2:3], s[56:57], 0, v[198:199]
	s_add_i32 m0, s48, 0x20000
	s_and_b64 vcc, exec, s[2:3]
	v_lshl_add_u64 v[2:3], s[56:57], 0, v[196:197]
	s_add_i32 m0, s48, 0x22000
	s_nop 0
	v_lshl_add_u64 v[2:3], v[206:207], 0, s[16:17]
	s_add_i32 m0, s48, 0xc000
	s_nop 0
	global_load_lds_dwordx4 v[2:3], off
	v_lshl_add_u64 v[2:3], v[208:209], 0, s[16:17]
	s_add_i32 m0, s48, 0xe000
	s_nop 0
	global_load_lds_dwordx4 v[2:3], off
	s_add_u32 s34, s34, 0x100
	s_addc_u32 s35, s35, 0
	s_add_u32 s18, s18, 0x100
	s_addc_u32 s41, s41, 0
	s_branch .Lq5_top

.Lq5_top:
	ds_read_b128 v[148:151], v214
	ds_read_b128 v[152:155], v214 offset:1024
	ds_read_b128 v[156:159], v214 offset:2048
	ds_read_b128 v[160:163], v214 offset:3072
	v_lshl_add_u64 v[2:3], s[34:35], 0, v[200:201]
	s_add_i32 m0, s48, 0xc000
	ds_read_b128 v[188:191], v216
	ds_read_b128 v[192:195], v216 offset:1024
	ds_read_b128 v[180:183], v216 offset:2048
	ds_read_b128 v[184:187], v216 offset:3072
	ds_read_b128 v[172:175], v216 offset:4096
	ds_read_b128 v[176:179], v216 offset:5120
	ds_read_b128 v[164:167], v216 offset:6144
	ds_read_b128 v[168:171], v216 offset:7168
	v_lshl_add_u64 v[2:3], s[34:35], 0, v[202:203]
	s_add_i32 m0, s48, 0xe000
	s_nop 0
	s_setprio 1
	v_mfma_f32_16x16x32_bf16 v[128:131], v[4:7], v[44:47], v[128:131]
	v_mfma_f32_16x16x32_bf16 v[124:127], v[12:15], v[44:47], v[124:127]
	v_mfma_f32_16x16x32_bf16 v[120:123], v[4:7], v[36:39], v[120:123]
	v_mfma_f32_16x16x32_bf16 v[116:119], v[12:15], v[36:39], v[116:119]
	v_mfma_f32_16x16x32_bf16 v[104:107], v[4:7], v[28:31], v[104:107]
	v_mfma_f32_16x16x32_bf16 v[100:103], v[12:15], v[28:31], v[100:103]
	s_setprio 0
	s_barrier
	v_cmp_ne_u32_e64 s[2:3], 1, v217
	s_andn2_b64 vcc, exec, s[26:27]
	s_add_u32 s56, s34, 0xfff80080
	s_addc_u32 s57, s35, -1
	s_cmp_eq_u32 s77, 10
	s_cselect_b32 s59, s39, s57
	s_cselect_b32 s58, s38, s56
	s_cselect_b32 s57, s47, s41
	s_cselect_b32 s56, s46, s18
	s_setprio 1
	v_mfma_f32_16x16x32_bf16 v[88:91], v[4:7], v[20:23], v[88:91]
	v_mfma_f32_16x16x32_bf16 v[84:87], v[12:15], v[20:23], v[84:87]
	v_mfma_f32_16x16x32_bf16 v[128:131], v[8:11], v[48:51], v[128:131]
	v_mfma_f32_16x16x32_bf16 v[124:127], v[16:19], v[48:51], v[124:127]
	v_mfma_f32_16x16x32_bf16 v[120:123], v[8:11], v[40:43], v[120:123]
	v_mfma_f32_16x16x32_bf16 v[116:119], v[16:19], v[40:43], v[116:119]
	s_setprio 0
	s_waitcnt lgkmcnt(0)
	s_barrier
	s_setprio 1
	v_mfma_f32_16x16x32_bf16 v[104:107], v[8:11], v[32:35], v[104:107]
	v_mfma_f32_16x16x32_bf16 v[100:103], v[16:19], v[32:35], v[100:103]
	v_mfma_f32_16x16x32_bf16 v[88:91], v[8:11], v[24:27], v[88:91]
	v_mfma_f32_16x16x32_bf16 v[84:87], v[16:19], v[24:27], v[84:87]
	s_setprio 0
	s_waitcnt vmcnt(8)
	s_barrier
	s_mov_b32 m0, s49
	v_lshl_add_u64 v[2:3], s[56:57], 0, v[198:199]
	s_add_u32 s78, s56, 0x80000
	global_load_lds_dwordx4 v[2:3], off
	v_lshl_add_u64 v[204:205], s[56:57], 0, v[196:197]
	s_mov_b32 m0, s50
	s_addc_u32 s79, s57, 0
	global_load_lds_dwordx4 v[204:205], off
	v_lshl_add_u64 v[206:207], s[78:79], 0, v[198:199]
	s_mov_b32 m0, s51
	v_lshl_add_u64 v[208:209], s[58:59], 0, v[196:197]
	v_lshl_add_u64 v[206:207], s[78:79], 0, v[196:197]
	s_mov_b32 m0, s60
	s_and_b64 vcc, exec, s[2:3]
	v_lshl_add_u64 v[206:207], s[58:59], 0, v[198:199]
	s_mov_b32 m0, s48
	s_nop 0
	global_load_lds_dwordx4 v[206:207], off
	s_mov_b32 m0, s61
	s_nop 0
	global_load_lds_dwordx4 v[208:209], off
	s_barrier
	v_add_u32_e32 v1, 0x18000, v213
	ds_read_b128 v[4:7], v1
	ds_read_b128 v[8:11], v1 offset:1024
	ds_read_b128 v[12:15], v1 offset:2048
	ds_read_b128 v[16:19], v1 offset:3072
	v_add_u32_e32 v1, 0x1c000, v213
	s_add_u32 s58, s58, 0x80000
	s_addc_u32 s59, s59, 0
	s_mov_b32 m0, s62
	v_lshl_add_u64 v[218:219], s[58:59], 0, v[198:199]
	ds_read_b128 v[44:47], v216 offset:32768
	ds_read_b128 v[48:51], v216 offset:33792
	ds_read_b128 v[36:39], v216 offset:34816
	ds_read_b128 v[40:43], v216 offset:35840
	ds_read_b128 v[28:31], v216 offset:36864
	ds_read_b128 v[32:35], v216 offset:37888
	ds_read_b128 v[20:23], v216 offset:38912
	ds_read_b128 v[24:27], v216 offset:39936
	v_lshl_add_u64 v[218:219], s[58:59], 0, v[196:197]
	s_mov_b32 m0, s63
	s_nop 0
	s_setprio 1
	v_mfma_f32_16x16x32_bf16 v[128:131], v[148:151], v[188:191], v[128:131]
	v_mfma_f32_16x16x32_bf16 v[124:127], v[156:159], v[188:191], v[124:127]
	v_mfma_f32_16x16x32_bf16 v[120:123], v[148:151], v[180:183], v[120:123]
	v_mfma_f32_16x16x32_bf16 v[116:119], v[156:159], v[180:183], v[116:119]
	v_mfma_f32_16x16x32_bf16 v[104:107], v[148:151], v[172:175], v[104:107]
	v_mfma_f32_16x16x32_bf16 v[100:103], v[156:159], v[172:175], v[100:103]
	s_setprio 0
	s_barrier
	s_and_b64 vcc, exec, s[2:3]
	s_setprio 1
	v_mfma_f32_16x16x32_bf16 v[88:91], v[148:151], v[164:167], v[88:91]
	v_mfma_f32_16x16x32_bf16 v[84:87], v[156:159], v[164:167], v[84:87]
	v_mfma_f32_16x16x32_bf16 v[128:131], v[152:155], v[192:195], v[128:131]
	v_mfma_f32_16x16x32_bf16 v[124:127], v[160:163], v[192:195], v[124:127]
	v_mfma_f32_16x16x32_bf16 v[120:123], v[152:155], v[184:187], v[120:123]
	v_mfma_f32_16x16x32_bf16 v[116:119], v[160:163], v[184:187], v[116:119]
	s_setprio 0
	s_waitcnt lgkmcnt(0)
	s_barrier
	s_setprio 1
	v_mfma_f32_16x16x32_bf16 v[104:107], v[152:155], v[176:179], v[104:107]
	v_mfma_f32_16x16x32_bf16 v[100:103], v[160:163], v[176:179], v[100:103]
	v_mfma_f32_16x16x32_bf16 v[88:91], v[152:155], v[168:171], v[88:91]
	v_mfma_f32_16x16x32_bf16 v[84:87], v[160:163], v[168:171], v[84:87]
	s_setprio 0
	s_waitcnt vmcnt(8)
	s_barrier
	s_mov_b32 m0, s66
	v_lshl_add_u64 v[2:3], v[2:3], 0, s[16:17]
	s_add_u32 s56, s56, 0x80080
	global_load_lds_dwordx4 v[2:3], off
	v_lshl_add_u64 v[2:3], v[204:205], 0, s[16:17]
	s_mov_b32 m0, s67
	s_addc_u32 s57, s57, 0
	global_load_lds_dwordx4 v[2:3], off
	v_lshl_add_u64 v[2:3], s[56:57], 0, v[198:199]
	s_mov_b32 m0, s70
	s_and_b64 vcc, exec, s[2:3]
	v_lshl_add_u64 v[2:3], s[56:57], 0, v[196:197]
	s_mov_b32 m0, s71
	s_nop 0
	v_lshl_add_u64 v[2:3], v[206:207], 0, s[16:17]
	s_mov_b32 m0, s68
	s_nop 0
	global_load_lds_dwordx4 v[2:3], off
	v_lshl_add_u64 v[2:3], v[208:209], 0, s[16:17]
	s_mov_b32 m0, s69
	s_nop 0
	global_load_lds_dwordx4 v[2:3], off
	s_barrier
	s_add_i32 s77, s77, 2
	s_add_u32 s34, s34, 0x100
	s_addc_u32 s35, s35, 0
	s_add_u32 s18, s18, 0x100
	s_addc_u32 s41, s41, 0
	s_cmp_gt_u32 s77, 13
	ds_read_b128 v[148:151], v215
	ds_read_b128 v[152:155], v215 offset:1024
	ds_read_b128 v[156:159], v215 offset:2048
	ds_read_b128 v[160:163], v215 offset:3072
	v_lshl_add_u64 v[2:3], s[34:35], 0, v[200:201]
	s_add_i32 m0, s48, 0xc000
	ds_read_b128 v[188:191], v216 offset:16384
	ds_read_b128 v[192:195], v216 offset:17408
	ds_read_b128 v[180:183], v216 offset:18432
	ds_read_b128 v[184:187], v216 offset:19456
	ds_read_b128 v[172:175], v216 offset:20480
	ds_read_b128 v[176:179], v216 offset:21504
	ds_read_b128 v[164:167], v216 offset:22528
	ds_read_b128 v[168:171], v216 offset:23552
	v_lshl_add_u64 v[2:3], s[34:35], 0, v[202:203]
	s_add_i32 m0, s48, 0xe000
	s_nop 0
	s_setprio 1
	v_mfma_f32_16x16x32_bf16 v[128:131], v[4:7], v[44:47], v[128:131]
	v_mfma_f32_16x16x32_bf16 v[124:127], v[12:15], v[44:47], v[124:127]
	v_mfma_f32_16x16x32_bf16 v[120:123], v[4:7], v[36:39], v[120:123]
	v_mfma_f32_16x16x32_bf16 v[116:119], v[12:15], v[36:39], v[116:119]
	v_mfma_f32_16x16x32_bf16 v[104:107], v[4:7], v[28:31], v[104:107]
	v_mfma_f32_16x16x32_bf16 v[100:103], v[12:15], v[28:31], v[100:103]
	s_setprio 0
	s_barrier
	v_cmp_ne_u32_e64 s[2:3], 1, v217
	s_andn2_b64 vcc, exec, s[26:27]
	s_add_u32 s56, s34, 0xfff80080
	s_addc_u32 s57, s35, -1
	s_cmp_eq_u32 s77, 12
	s_cselect_b32 s59, s39, s57
	s_cselect_b32 s58, s38, s56
	s_cselect_b32 s57, s47, s41
	s_cselect_b32 s56, s46, s18
	s_setprio 1
	v_mfma_f32_16x16x32_bf16 v[88:91], v[4:7], v[20:23], v[88:91]
	v_mfma_f32_16x16x32_bf16 v[84:87], v[12:15], v[20:23], v[84:87]
	v_mfma_f32_16x16x32_bf16 v[128:131], v[8:11], v[48:51], v[128:131]
	v_mfma_f32_16x16x32_bf16 v[124:127], v[16:19], v[48:51], v[124:127]
	v_mfma_f32_16x16x32_bf16 v[120:123], v[8:11], v[40:43], v[120:123]
	v_mfma_f32_16x16x32_bf16 v[116:119], v[16:19], v[40:43], v[116:119]
	s_setprio 0
	s_waitcnt lgkmcnt(0)
	s_barrier
	s_setprio 1
	v_mfma_f32_16x16x32_bf16 v[104:107], v[8:11], v[32:35], v[104:107]
	v_mfma_f32_16x16x32_bf16 v[100:103], v[16:19], v[32:35], v[100:103]
	v_mfma_f32_16x16x32_bf16 v[88:91], v[8:11], v[24:27], v[88:91]
	v_mfma_f32_16x16x32_bf16 v[84:87], v[16:19], v[24:27], v[84:87]
	s_setprio 0
	s_waitcnt vmcnt(8)
	s_barrier
	s_cmp_eq_u32 s77, 12
	s_cbranch_scc1 .Lq5_o_n0
	s_mov_b32 m0, s51
	v_lshl_add_u64 v[2:3], s[56:57], 0, v[198:199]
	s_add_u32 s78, s56, 0x80000
	global_load_lds_dwordx4 v[2:3], off
	v_lshl_add_u64 v[204:205], s[56:57], 0, v[196:197]
	s_mov_b32 m0, s60
	s_addc_u32 s79, s57, 0
	global_load_lds_dwordx4 v[204:205], off
	v_lshl_add_u64 v[206:207], s[78:79], 0, v[198:199]
	s_mov_b32 m0, s66
	v_lshl_add_u64 v[208:209], s[58:59], 0, v[196:197]
	v_lshl_add_u64 v[206:207], s[78:79], 0, v[196:197]
	s_mov_b32 m0, s67
	s_and_b64 vcc, exec, s[2:3]
	v_lshl_add_u64 v[206:207], s[58:59], 0, v[198:199]
	s_mov_b32 m0, s62
	s_nop 0
	global_load_lds_dwordx4 v[206:207], off
	s_mov_b32 m0, s63
	s_nop 0
	global_load_lds_dwordx4 v[208:209], off
.Lq5_o_n0:
	s_barrier
	v_add_u32_e32 v1, 0x1c000, v213
	ds_read_b128 v[4:7], v1
	ds_read_b128 v[8:11], v1 offset:1024
	ds_read_b128 v[12:15], v1 offset:2048
	ds_read_b128 v[16:19], v1 offset:3072
	v_add_u32_e32 v1, 0x1c000, v213
	s_add_u32 s58, s58, 0x80000
	s_addc_u32 s59, s59, 0
	s_mov_b32 m0, s62
	v_lshl_add_u64 v[218:219], s[58:59], 0, v[198:199]
	ds_read_b128 v[44:47], v216 offset:49152
	ds_read_b128 v[48:51], v216 offset:50176
	ds_read_b128 v[36:39], v216 offset:51200
	ds_read_b128 v[40:43], v216 offset:52224
	ds_read_b128 v[28:31], v216 offset:53248
	ds_read_b128 v[32:35], v216 offset:54272
	ds_read_b128 v[20:23], v216 offset:55296
	ds_read_b128 v[24:27], v216 offset:56320
	v_lshl_add_u64 v[218:219], s[58:59], 0, v[196:197]
	s_mov_b32 m0, s63
	s_nop 0
	s_setprio 1
	v_mfma_f32_16x16x32_bf16 v[128:131], v[148:151], v[188:191], v[128:131]
	v_mfma_f32_16x16x32_bf16 v[124:127], v[156:159], v[188:191], v[124:127]
	v_mfma_f32_16x16x32_bf16 v[120:123], v[148:151], v[180:183], v[120:123]
	v_mfma_f32_16x16x32_bf16 v[116:119], v[156:159], v[180:183], v[116:119]
	v_mfma_f32_16x16x32_bf16 v[104:107], v[148:151], v[172:175], v[104:107]
	v_mfma_f32_16x16x32_bf16 v[100:103], v[156:159], v[172:175], v[100:103]
	s_setprio 0
	s_barrier
	s_and_b64 vcc, exec, s[2:3]
	s_setprio 1
	v_mfma_f32_16x16x32_bf16 v[88:91], v[148:151], v[164:167], v[88:91]
	v_mfma_f32_16x16x32_bf16 v[84:87], v[156:159], v[164:167], v[84:87]
	v_mfma_f32_16x16x32_bf16 v[128:131], v[152:155], v[192:195], v[128:131]
	v_mfma_f32_16x16x32_bf16 v[124:127], v[160:163], v[192:195], v[124:127]
	v_mfma_f32_16x16x32_bf16 v[120:123], v[152:155], v[184:187], v[120:123]
	v_mfma_f32_16x16x32_bf16 v[116:119], v[160:163], v[184:187], v[116:119]
	s_setprio 0
	s_waitcnt lgkmcnt(0)
	s_barrier
	s_setprio 1
	v_mfma_f32_16x16x32_bf16 v[104:107], v[152:155], v[176:179], v[104:107]
	v_mfma_f32_16x16x32_bf16 v[100:103], v[160:163], v[176:179], v[100:103]
	v_mfma_f32_16x16x32_bf16 v[88:91], v[152:155], v[168:171], v[88:91]
	v_mfma_f32_16x16x32_bf16 v[84:87], v[160:163], v[168:171], v[84:87]
	s_setprio 0
	s_waitcnt vmcnt(8)
	s_cmp_eq_u32 s77, 12
	s_cbranch_scc0 .Lq5_o_w
	s_waitcnt vmcnt(4)
.Lq5_o_w:
	s_barrier
	s_cmp_eq_u32 s77, 12
	s_cbranch_scc1 .Lq5_o_n1
	s_mov_b32 m0, s70
	v_lshl_add_u64 v[2:3], v[2:3], 0, s[16:17]
	s_add_u32 s56, s56, 0x80080
	global_load_lds_dwordx4 v[2:3], off
	v_lshl_add_u64 v[2:3], v[204:205], 0, s[16:17]
	s_mov_b32 m0, s71
	s_addc_u32 s57, s57, 0
	global_load_lds_dwordx4 v[2:3], off
	v_lshl_add_u64 v[2:3], s[56:57], 0, v[198:199]
	s_add_i32 m0, s48, 0x20000
	s_and_b64 vcc, exec, s[2:3]
	v_lshl_add_u64 v[2:3], s[56:57], 0, v[196:197]
	s_add_i32 m0, s48, 0x22000
	s_nop 0
	v_lshl_add_u64 v[2:3], v[206:207], 0, s[16:17]
	s_add_i32 m0, s48, 0xc000
	s_nop 0
	global_load_lds_dwordx4 v[2:3], off
	v_lshl_add_u64 v[2:3], v[208:209], 0, s[16:17]
	s_add_i32 m0, s48, 0xe000
	s_nop 0
	global_load_lds_dwordx4 v[2:3], off
.Lq5_o_n1:
	s_branch .Lq5_be

.Lq6_entry:
	v_mov_b32_e32 v4, 0
	v_mov_b32_e32 v5, 0
	v_mov_b32_e32 v6, 0
	v_mov_b32_e32 v7, 0
	v_mov_b32_e32 v8, 0
	v_mov_b32_e32 v9, 0
	v_mov_b32_e32 v10, 0
	v_mov_b32_e32 v11, 0
	v_mov_b32_e32 v12, 0
	v_mov_b32_e32 v13, 0
	v_mov_b32_e32 v14, 0
	v_mov_b32_e32 v15, 0
	v_mov_b32_e32 v16, 0
	v_mov_b32_e32 v17, 0
	v_mov_b32_e32 v18, 0
	v_mov_b32_e32 v19, 0
	v_mov_b32_e32 v20, 0
	v_mov_b32_e32 v21, 0
	v_mov_b32_e32 v22, 0
	v_mov_b32_e32 v23, 0
	v_mov_b32_e32 v24, 0
	v_mov_b32_e32 v25, 0
	v_mov_b32_e32 v26, 0
	v_mov_b32_e32 v27, 0
	v_mov_b32_e32 v28, 0
	v_mov_b32_e32 v29, 0
	v_mov_b32_e32 v30, 0
	v_mov_b32_e32 v31, 0
	v_mov_b32_e32 v32, 0
	v_mov_b32_e32 v33, 0
	v_mov_b32_e32 v34, 0
	v_mov_b32_e32 v35, 0
	v_mov_b32_e32 v36, 0
	v_mov_b32_e32 v37, 0
	v_mov_b32_e32 v38, 0
	v_mov_b32_e32 v39, 0
	v_mov_b32_e32 v40, 0
	v_mov_b32_e32 v41, 0
	v_mov_b32_e32 v42, 0
	v_mov_b32_e32 v43, 0
	v_mov_b32_e32 v44, 0
	v_mov_b32_e32 v45, 0
	v_mov_b32_e32 v46, 0
	v_mov_b32_e32 v47, 0
	v_mov_b32_e32 v48, 0
	v_mov_b32_e32 v49, 0
	v_mov_b32_e32 v50, 0
	v_mov_b32_e32 v51, 0
	v_cmp_ne_u32_e64 s[4:5], 1, v251
	s_andn2_b64 vcc, exec, s[34:35]
	s_add_u32 s40, s38, 0xfff80080
	s_addc_u32 s41, s39, -1
	s_cmp_eq_u32 s84, 28
	s_cselect_b32 s47, s29, s41
	s_cselect_b32 s46, s28, s40
	s_cselect_b32 s41, s37, s27
	s_cselect_b32 s40, s36, s16
	s_mov_b32 m0, s49
	v_lshl_add_u64 v[2:3], s[40:41], 0, v[230:231]
	s_add_u32 s86, s40, 0x80000
	global_load_lds_dwordx4 v[2:3], off
	v_lshl_add_u64 v[236:237], s[40:41], 0, v[228:229]
	s_mov_b32 m0, s50
	s_addc_u32 s87, s41, 0
	global_load_lds_dwordx4 v[236:237], off
	v_lshl_add_u64 v[54:55], s[86:87], 0, v[230:231]
	s_mov_b32 m0, s61
	v_lshl_add_u64 v[238:239], s[46:47], 0, v[230:231]
	v_lshl_add_u64 v[54:55], s[86:87], 0, v[228:229]
	s_mov_b32 m0, s62
	v_lshl_add_u64 v[240:241], s[46:47], 0, v[228:229]
	s_mov_b32 m0, s56
	s_and_b64 vcc, exec, s[4:5]
	global_load_lds_dwordx4 v[238:239], off
	s_mov_b32 m0, s57
	s_nop 0
	global_load_lds_dwordx4 v[240:241], off
	s_and_b64 vcc, exec, s[4:5]
	s_mov_b32 m0, s65
	v_lshl_add_u64 v[2:3], v[2:3], 0, s[14:15]
	s_add_u32 s40, s40, 0x80080
	global_load_lds_dwordx4 v[2:3], off
	v_lshl_add_u64 v[2:3], v[236:237], 0, s[14:15]
	s_mov_b32 m0, s66
	s_addc_u32 s41, s41, 0
	global_load_lds_dwordx4 v[2:3], off
	v_lshl_add_u64 v[2:3], s[40:41], 0, v[230:231]
	s_add_i32 m0, s44, 0x20000
	s_and_b64 vcc, exec, s[4:5]
	v_lshl_add_u64 v[2:3], s[40:41], 0, v[228:229]
	s_add_i32 m0, s44, 0x22000
	s_nop 0
	v_lshl_add_u64 v[2:3], v[238:239], 0, s[14:15]
	s_add_i32 m0, s44, 0xc000
	s_nop 0
	global_load_lds_dwordx4 v[2:3], off
	v_lshl_add_u64 v[2:3], v[240:241], 0, s[14:15]
	s_add_i32 m0, s44, 0xe000
	s_nop 0
	global_load_lds_dwordx4 v[2:3], off
	s_add_u32 s38, s38, 0x100
	s_addc_u32 s39, s39, 0
	s_add_u32 s16, s16, 0x100
	s_addc_u32 s27, s27, 0
	s_branch .Lq6_top

.Lq6_top:
	ds_read_b128 v[180:183], v247
	ds_read_b128 v[184:187], v247 offset:1024
	ds_read_b128 v[188:191], v247 offset:2048
	ds_read_b128 v[192:195], v247 offset:3072
	v_lshl_add_u64 v[2:3], s[38:39], 0, v[232:233]
	s_add_i32 m0, s44, 0xc000
	ds_read_b128 v[220:223], v249
	ds_read_b128 v[224:227], v249 offset:1024
	ds_read_b128 v[212:215], v249 offset:2048
	ds_read_b128 v[216:219], v249 offset:3072
	ds_read_b128 v[204:207], v249 offset:4096
	ds_read_b128 v[208:211], v249 offset:5120
	ds_read_b128 v[196:199], v249 offset:6144
	ds_read_b128 v[200:203], v249 offset:7168
	v_lshl_add_u64 v[2:3], s[38:39], 0, v[234:235]
	s_add_i32 m0, s44, 0xe000
	s_nop 0
	s_setprio 1
	v_mfma_f32_16x16x32_bf16 v[68:71], v[4:7], v[44:47], v[160:163]
	v_mfma_f32_16x16x32_bf16 v[72:75], v[12:15], v[44:47], v[156:159]
	v_mfma_f32_16x16x32_bf16 v[76:79], v[4:7], v[36:39], v[152:155]
	v_mfma_f32_16x16x32_bf16 v[80:83], v[12:15], v[36:39], v[148:151]
	v_mfma_f32_16x16x32_bf16 v[84:87], v[4:7], v[28:31], v[136:139]
	v_mfma_f32_16x16x32_bf16 v[92:95], v[12:15], v[28:31], v[132:135]
	s_setprio 0
	s_barrier
	v_cmp_ne_u32_e64 s[4:5], 1, v251
	s_andn2_b64 vcc, exec, s[34:35]
	s_add_u32 s40, s38, 0xfff80080
	s_addc_u32 s41, s39, -1
	s_cmp_eq_u32 s84, 26
	s_cselect_b32 s47, s29, s41
	s_cselect_b32 s46, s28, s40
	s_cselect_b32 s41, s37, s27
	s_cselect_b32 s40, s36, s16
	s_setprio 1
	v_mfma_f32_16x16x32_bf16 v[96:99], v[4:7], v[20:23], v[120:123]
	v_mfma_f32_16x16x32_bf16 v[100:103], v[12:15], v[20:23], v[112:115]
	v_mfma_f32_16x16x32_bf16 v[68:71], v[8:11], v[48:51], v[68:71]
	v_mfma_f32_16x16x32_bf16 v[72:75], v[16:19], v[48:51], v[72:75]
	v_mfma_f32_16x16x32_bf16 v[76:79], v[8:11], v[40:43], v[76:79]
	v_mfma_f32_16x16x32_bf16 v[80:83], v[16:19], v[40:43], v[80:83]
	s_setprio 0
	s_waitcnt lgkmcnt(0)
	s_barrier
	s_setprio 1
	v_mfma_f32_16x16x32_bf16 v[84:87], v[8:11], v[32:35], v[84:87]
	v_mfma_f32_16x16x32_bf16 v[92:95], v[16:19], v[32:35], v[92:95]
	v_mfma_f32_16x16x32_bf16 v[96:99], v[8:11], v[24:27], v[96:99]
	v_mfma_f32_16x16x32_bf16 v[100:103], v[16:19], v[24:27], v[100:103]
	s_setprio 0
	s_waitcnt vmcnt(8)
	s_barrier
	s_mov_b32 m0, s45
	v_lshl_add_u64 v[2:3], s[40:41], 0, v[230:231]
	s_add_u32 s86, s40, 0x80000
	global_load_lds_dwordx4 v[2:3], off
	v_lshl_add_u64 v[236:237], s[40:41], 0, v[228:229]
	s_mov_b32 m0, s48
	s_addc_u32 s87, s41, 0
	global_load_lds_dwordx4 v[236:237], off
	v_lshl_add_u64 v[54:55], s[86:87], 0, v[230:231]
	s_mov_b32 m0, s49
	v_lshl_add_u64 v[238:239], s[46:47], 0, v[230:231]
	v_lshl_add_u64 v[54:55], s[86:87], 0, v[228:229]
	s_mov_b32 m0, s50
	v_lshl_add_u64 v[240:241], s[46:47], 0, v[228:229]
	s_mov_b32 m0, s44
	s_and_b64 vcc, exec, s[4:5]
	global_load_lds_dwordx4 v[238:239], off
	s_mov_b32 m0, s51
	s_nop 0
	global_load_lds_dwordx4 v[240:241], off
	s_barrier
	v_add_u32_e32 v1, 0x18000, v246
	ds_read_b128 v[4:7], v1
	ds_read_b128 v[8:11], v1 offset:1024
	ds_read_b128 v[12:15], v1 offset:2048
	ds_read_b128 v[16:19], v1 offset:3072
	v_add_u32_e32 v1, 0x1c000, v246
	s_add_u32 s46, s46, 0x80000
	s_addc_u32 s47, s47, 0
	s_mov_b32 m0, s56
	v_lshl_add_u64 v[112:113], s[46:47], 0, v[230:231]
	ds_read_b128 v[44:47], v249 offset:32768
	ds_read_b128 v[48:51], v249 offset:33792
	ds_read_b128 v[36:39], v249 offset:34816
	ds_read_b128 v[40:43], v249 offset:35840
	ds_read_b128 v[28:31], v249 offset:36864
	ds_read_b128 v[32:35], v249 offset:37888
	ds_read_b128 v[20:23], v249 offset:38912
	ds_read_b128 v[24:27], v249 offset:39936
	v_lshl_add_u64 v[112:113], s[46:47], 0, v[228:229]
	s_mov_b32 m0, s57
	s_nop 0
	s_setprio 1
	v_mfma_f32_16x16x32_bf16 v[68:71], v[180:183], v[220:223], v[68:71]
	v_mfma_f32_16x16x32_bf16 v[160:163], v[184:187], v[224:227], v[68:71]
	v_mfma_f32_16x16x32_bf16 v[68:71], v[188:191], v[220:223], v[72:75]
	v_mfma_f32_16x16x32_bf16 v[156:159], v[192:195], v[224:227], v[68:71]
	v_mfma_f32_16x16x32_bf16 v[68:71], v[180:183], v[212:215], v[76:79]
	v_mfma_f32_16x16x32_bf16 v[152:155], v[184:187], v[216:219], v[68:71]
	s_setprio 0
	s_barrier
	s_and_b64 vcc, exec, s[4:5]
	s_setprio 1
	v_mfma_f32_16x16x32_bf16 v[68:71], v[188:191], v[212:215], v[80:83]
	v_mfma_f32_16x16x32_bf16 v[148:151], v[192:195], v[216:219], v[68:71]
	v_mfma_f32_16x16x32_bf16 v[68:71], v[180:183], v[204:207], v[84:87]
	v_mfma_f32_16x16x32_bf16 v[136:139], v[184:187], v[208:211], v[68:71]
	v_mfma_f32_16x16x32_bf16 v[68:71], v[188:191], v[204:207], v[92:95]
	v_mfma_f32_16x16x32_bf16 v[132:135], v[192:195], v[208:211], v[68:71]
	s_setprio 0
	s_waitcnt lgkmcnt(0)
	s_barrier
	s_setprio 1
	v_mfma_f32_16x16x32_bf16 v[68:71], v[180:183], v[196:199], v[96:99]
	v_mfma_f32_16x16x32_bf16 v[120:123], v[184:187], v[200:203], v[68:71]
	v_mfma_f32_16x16x32_bf16 v[68:71], v[188:191], v[196:199], v[100:103]
	v_mfma_f32_16x16x32_bf16 v[112:115], v[192:195], v[200:203], v[68:71]
	s_setprio 0
	s_waitcnt vmcnt(8)
	s_barrier
	s_mov_b32 m0, s61
	v_lshl_add_u64 v[2:3], v[2:3], 0, s[14:15]
	s_add_u32 s40, s40, 0x80080
	global_load_lds_dwordx4 v[2:3], off
	v_lshl_add_u64 v[2:3], v[236:237], 0, s[14:15]
	s_mov_b32 m0, s62
	s_addc_u32 s41, s41, 0
	global_load_lds_dwordx4 v[2:3], off
	v_lshl_add_u64 v[2:3], s[40:41], 0, v[230:231]
	s_mov_b32 m0, s65
	s_and_b64 vcc, exec, s[4:5]
	v_lshl_add_u64 v[2:3], s[40:41], 0, v[228:229]
	s_mov_b32 m0, s66
	s_nop 0
	v_lshl_add_u64 v[2:3], v[238:239], 0, s[14:15]
	s_mov_b32 m0, s63
	s_nop 0
	global_load_lds_dwordx4 v[2:3], off
	v_lshl_add_u64 v[2:3], v[240:241], 0, s[14:15]
	s_mov_b32 m0, s64
	s_nop 0
	global_load_lds_dwordx4 v[2:3], off
	s_barrier
	s_add_i32 s84, s84, 2
	s_add_u32 s38, s38, 0x100
	s_addc_u32 s39, s39, 0
	s_add_u32 s16, s16, 0x100
	s_addc_u32 s27, s27, 0
	s_cmp_gt_u32 s84, 29
	ds_read_b128 v[180:183], v248
	ds_read_b128 v[184:187], v248 offset:1024
	ds_read_b128 v[188:191], v248 offset:2048
	ds_read_b128 v[192:195], v248 offset:3072
	v_lshl_add_u64 v[2:3], s[38:39], 0, v[232:233]
	s_add_i32 m0, s44, 0xc000
	ds_read_b128 v[220:223], v249 offset:16384
	ds_read_b128 v[224:227], v249 offset:17408
	ds_read_b128 v[212:215], v249 offset:18432
	ds_read_b128 v[216:219], v249 offset:19456
	ds_read_b128 v[204:207], v249 offset:20480
	ds_read_b128 v[208:211], v249 offset:21504
	ds_read_b128 v[196:199], v249 offset:22528
	ds_read_b128 v[200:203], v249 offset:23552
	v_lshl_add_u64 v[2:3], s[38:39], 0, v[234:235]
	s_add_i32 m0, s44, 0xe000
	s_nop 0
	s_setprio 1
	v_mfma_f32_16x16x32_bf16 v[68:71], v[4:7], v[44:47], v[160:163]
	v_mfma_f32_16x16x32_bf16 v[72:75], v[12:15], v[44:47], v[156:159]
	v_mfma_f32_16x16x32_bf16 v[76:79], v[4:7], v[36:39], v[152:155]
	v_mfma_f32_16x16x32_bf16 v[80:83], v[12:15], v[36:39], v[148:151]
	v_mfma_f32_16x16x32_bf16 v[84:87], v[4:7], v[28:31], v[136:139]
	v_mfma_f32_16x16x32_bf16 v[92:95], v[12:15], v[28:31], v[132:135]
	s_setprio 0
	s_barrier
	v_cmp_ne_u32_e64 s[4:5], 1, v251
	s_andn2_b64 vcc, exec, s[34:35]
	s_add_u32 s40, s38, 0xfff80080
	s_addc_u32 s41, s39, -1
	s_cmp_eq_u32 s84, 28
	s_cselect_b32 s47, s29, s41
	s_cselect_b32 s46, s28, s40
	s_cselect_b32 s41, s37, s27
	s_cselect_b32 s40, s36, s16
	s_setprio 1
	v_mfma_f32_16x16x32_bf16 v[96:99], v[4:7], v[20:23], v[120:123]
	v_mfma_f32_16x16x32_bf16 v[100:103], v[12:15], v[20:23], v[112:115]
	v_mfma_f32_16x16x32_bf16 v[68:71], v[8:11], v[48:51], v[68:71]
	v_mfma_f32_16x16x32_bf16 v[72:75], v[16:19], v[48:51], v[72:75]
	v_mfma_f32_16x16x32_bf16 v[76:79], v[8:11], v[40:43], v[76:79]
	v_mfma_f32_16x16x32_bf16 v[80:83], v[16:19], v[40:43], v[80:83]
	s_setprio 0
	s_waitcnt lgkmcnt(0)
	s_barrier
	s_setprio 1
	v_mfma_f32_16x16x32_bf16 v[84:87], v[8:11], v[32:35], v[84:87]
	v_mfma_f32_16x16x32_bf16 v[92:95], v[16:19], v[32:35], v[92:95]
	v_mfma_f32_16x16x32_bf16 v[96:99], v[8:11], v[24:27], v[96:99]
	v_mfma_f32_16x16x32_bf16 v[100:103], v[16:19], v[24:27], v[100:103]
	s_setprio 0
	s_waitcnt vmcnt(8)
	s_barrier
	s_cmp_eq_u32 s84, 28
	s_cbranch_scc1 .Lq6_o_n0
	s_mov_b32 m0, s49
	v_lshl_add_u64 v[2:3], s[40:41], 0, v[230:231]
	s_add_u32 s86, s40, 0x80000
	global_load_lds_dwordx4 v[2:3], off
	v_lshl_add_u64 v[236:237], s[40:41], 0, v[228:229]
	s_mov_b32 m0, s50
	s_addc_u32 s87, s41, 0
	global_load_lds_dwordx4 v[236:237], off
	v_lshl_add_u64 v[54:55], s[86:87], 0, v[230:231]
	s_mov_b32 m0, s61
	v_lshl_add_u64 v[238:239], s[46:47], 0, v[230:231]
	v_lshl_add_u64 v[54:55], s[86:87], 0, v[228:229]
	s_mov_b32 m0, s62
	v_lshl_add_u64 v[240:241], s[46:47], 0, v[228:229]
	s_mov_b32 m0, s56
	s_and_b64 vcc, exec, s[4:5]
	global_load_lds_dwordx4 v[238:239], off
	s_mov_b32 m0, s57
	s_nop 0
	global_load_lds_dwordx4 v[240:241], off
.Lq6_o_n0:
	s_barrier
	v_add_u32_e32 v1, 0x1c000, v246
	ds_read_b128 v[4:7], v1
	ds_read_b128 v[8:11], v1 offset:1024
	ds_read_b128 v[12:15], v1 offset:2048
	ds_read_b128 v[16:19], v1 offset:3072
	v_add_u32_e32 v1, 0x1c000, v246
	s_add_u32 s46, s46, 0x80000
	s_addc_u32 s47, s47, 0
	s_mov_b32 m0, s56
	v_lshl_add_u64 v[112:113], s[46:47], 0, v[230:231]
	ds_read_b128 v[44:47], v249 offset:49152
	ds_read_b128 v[48:51], v249 offset:50176
	ds_read_b128 v[36:39], v249 offset:51200
	ds_read_b128 v[40:43], v249 offset:52224
	ds_read_b128 v[28:31], v249 offset:53248
	ds_read_b128 v[32:35], v249 offset:54272
	ds_read_b128 v[20:23], v249 offset:55296
	ds_read_b128 v[24:27], v249 offset:56320
	v_lshl_add_u64 v[112:113], s[46:47], 0, v[228:229]
	s_mov_b32 m0, s57
	s_nop 0
	s_setprio 1
	v_mfma_f32_16x16x32_bf16 v[68:71], v[180:183], v[220:223], v[68:71]
	v_mfma_f32_16x16x32_bf16 v[160:163], v[184:187], v[224:227], v[68:71]
	v_mfma_f32_16x16x32_bf16 v[68:71], v[188:191], v[220:223], v[72:75]
	v_mfma_f32_16x16x32_bf16 v[156:159], v[192:195], v[224:227], v[68:71]
	v_mfma_f32_16x16x32_bf16 v[68:71], v[180:183], v[212:215], v[76:79]
	v_mfma_f32_16x16x32_bf16 v[152:155], v[184:187], v[216:219], v[68:71]
	s_setprio 0
	s_barrier
	s_and_b64 vcc, exec, s[4:5]
	s_setprio 1
	v_mfma_f32_16x16x32_bf16 v[68:71], v[188:191], v[212:215], v[80:83]
	v_mfma_f32_16x16x32_bf16 v[148:151], v[192:195], v[216:219], v[68:71]
	v_mfma_f32_16x16x32_bf16 v[68:71], v[180:183], v[204:207], v[84:87]
	v_mfma_f32_16x16x32_bf16 v[136:139], v[184:187], v[208:211], v[68:71]
	v_mfma_f32_16x16x32_bf16 v[68:71], v[188:191], v[204:207], v[92:95]
	v_mfma_f32_16x16x32_bf16 v[132:135], v[192:195], v[208:211], v[68:71]
	s_setprio 0
	s_waitcnt lgkmcnt(0)
	s_barrier
	s_setprio 1
	v_mfma_f32_16x16x32_bf16 v[68:71], v[180:183], v[196:199], v[96:99]
	v_mfma_f32_16x16x32_bf16 v[120:123], v[184:187], v[200:203], v[68:71]
	v_mfma_f32_16x16x32_bf16 v[68:71], v[188:191], v[196:199], v[100:103]
	v_mfma_f32_16x16x32_bf16 v[112:115], v[192:195], v[200:203], v[68:71]
	s_setprio 0
	s_waitcnt vmcnt(8)
	s_cmp_eq_u32 s84, 28
	s_cbranch_scc0 .Lq6_o_w
	s_waitcnt vmcnt(4)
.Lq6_o_w:
	s_barrier
	s_cmp_eq_u32 s84, 28
	s_cbranch_scc1 .Lq6_o_n1
	s_mov_b32 m0, s65
	v_lshl_add_u64 v[2:3], v[2:3], 0, s[14:15]
	s_add_u32 s40, s40, 0x80080
	global_load_lds_dwordx4 v[2:3], off
	v_lshl_add_u64 v[2:3], v[236:237], 0, s[14:15]
	s_mov_b32 m0, s66
	s_addc_u32 s41, s41, 0
	global_load_lds_dwordx4 v[2:3], off
	v_lshl_add_u64 v[2:3], s[40:41], 0, v[230:231]
	s_add_i32 m0, s44, 0x20000
	s_and_b64 vcc, exec, s[4:5]
	v_lshl_add_u64 v[2:3], s[40:41], 0, v[228:229]
	s_add_i32 m0, s44, 0x22000
	s_nop 0
	v_lshl_add_u64 v[2:3], v[238:239], 0, s[14:15]
	s_add_i32 m0, s44, 0xc000
	s_nop 0
	global_load_lds_dwordx4 v[2:3], off
	v_lshl_add_u64 v[2:3], v[240:241], 0, s[14:15]
	s_add_i32 m0, s44, 0xe000
	s_nop 0
	global_load_lds_dwordx4 v[2:3], off
